# sample attention PV pass: 33rd row group issued with the batch, new-token V rows preloaded once (no per-iteration load/wait)
# speedup vs baseline: 1.0102x; 1.0009x over previous
; DI float bflo(unsigned w) { return __uint_as_float(w << 16); }
; DI float bfhi(unsigned w) { return __uint_as_float(w & 0xffff0000u); }
; #define LDS_WAIT() asm volatile("s_waitcnt lgkmcnt(0)" ::: "memory")
; DI void attn_sample_unit(const Params& p, int u, const bf16_t* Q, const bf16_t* Kb, const bf16_t* Vb, bf16_t* att, LAS float* sl, int lane) {
;     ...
;     ls = wave_sum(ls);
;     LDS_WAIT();
;     { const int kg = lane >> 4, d4 = lane & 15; f32x4 acc = (f32x4){0.f, 0.f, 0.f, 0.f};
;     ...
;         if (kg == 0) { for (int j = 0; dil * j <= t; ++j) { const int idx = 2048 + t - dil * j; const float pv = sl[64 + pat * 192 + j];
;             const u32x2 w = *(const u32x2*)(Vb + ((size_t)NP + b * 4 + (idx - 2048)) * 1024 + h * 64 + 4 * d4);
;             acc += (f32x4){bflo(w.x), bfhi(w.x), bflo(w.y), bfhi(w.y)} * pv; } } }
.LBB0_1533:
	ds_bpermute_b32 v0, v0, v5
	s_waitcnt lgkmcnt(0)
	s_or_b32 s84, s0, s4
	v_readlane_b32 s0, v254, 10
	s_lshl_b64 s[76:77], s[86:87], 15
	s_waitcnt lgkmcnt(0)
	v_add_f32_e32 v0, v5, v0
	ds_bpermute_b32 v1, v1, v0
	s_lshl_b32 s90, s0, 1
	v_mov_b32_e32 v140, 0
	s_or_b32 s76, s76, s5
	v_lshl_add_u64 v[138:139], v[136:137], 0, s[90:91]
	s_and_b32 s98, s84, -4
	s_add_i32 s100, s98, 0
	s_ashr_i32 s101, s100, 31
	s_lshl_b64 s[100:101], s[100:101], 11
	v_lshl_add_u64 v[236:237], v[138:139], 0, s[100:101]
	global_load_dwordx2 v[228:229], v[236:237], off
	s_add_i32 s100, s98, 1
	s_ashr_i32 s101, s100, 31
	s_lshl_b64 s[100:101], s[100:101], 11
	v_lshl_add_u64 v[236:237], v[138:139], 0, s[100:101]
	global_load_dwordx2 v[230:231], v[236:237], off
	s_add_i32 s100, s98, 2
	s_ashr_i32 s101, s100, 31
	s_lshl_b64 s[100:101], s[100:101], 11
	v_lshl_add_u64 v[236:237], v[138:139], 0, s[100:101]
	global_load_dwordx2 v[232:233], v[236:237], off
	s_add_i32 s100, s98, 3
	s_ashr_i32 s101, s100, 31
	s_lshl_b64 s[100:101], s[100:101], 11
	v_lshl_add_u64 v[236:237], v[138:139], 0, s[100:101]
	global_load_dwordx2 v[234:235], v[236:237], off
	s_waitcnt lgkmcnt(0)
	v_add_f32_e32 v0, v0, v1
	ds_bpermute_b32 v1, v2, v0
	s_mov_b32 s5, 0
	v_readlane_b32 s85, v254, 18
	v_mov_b32_e32 v141, v140
	v_mov_b32_e32 v142, v140
	s_waitcnt lgkmcnt(0)
	v_add_f32_e32 v0, v0, v1
	ds_bpermute_b32 v1, v3, v0
	v_mov_b32_e32 v143, v140
	s_waitcnt lgkmcnt(0)
	v_add_f32_e32 v0, v0, v1
	ds_bpermute_b32 v1, v213, v0
	s_waitcnt lgkmcnt(0)
	v_add_f32_e32 v215, v0, v1
	ds_bpermute_b32 v216, v214, v215
	s_branch .LBB0_1535

; DI void attn_sample_unit(const Params& p, int u, const bf16_t* Q, const bf16_t* Kb, const bf16_t* Vb, bf16_t* att, LAS float* sl, int lane) {
;     ...
;       for (int pat = 0; pat < 3; ++pat) { const int dil = 1 << (2 * pat);
; #pragma unroll
;         for (int jj = 0; jj < 33; ++jj) { const int j = kg + 4 * jj; int idx = 2048 + t - dil * j; const bool use = (j <= 128) && (idx < 2048);
;             idx = idx < 0 ? 0 : (idx > 2047 ? 2047 : idx); const float pv = use ? sl[64 + pat * 192 + (j > 128 ? 128 : j)] : 0.f;
;             const f32x4 vv = *(const f32x4*)(cv + (((size_t)b * 2048 + idx) * 16 + h) * 64 + 4 * d4);
;             acc += vv * pv; }
.LBB0_1535:
	s_lshl_b32 s86, s5, 1
	v_lshlrev_b32_e32 v0, s86, v147
	s_mul_i32 s0, s5, 0x300
	v_sub_u32_e32 v0, s2, v0
	s_add_i32 s0, s3, s0
	v_cmp_gt_i32_e32 vcc, s81, v0
	s_and_b64 s[78:79], s[8:9], vcc
	v_lshl_add_u32 v217, v147, 2, s0
	v_mov_b32_e32 v132, 0
	s_and_saveexec_b64 s[0:1], s[78:79]
	ds_read_b32 v132, v217 offset:256
	s_or_b64 exec, exec, s[0:1]
	v_med3_i32 v0, v0, 0, v212
	v_lshl_or_b32 v0, v0, 4, s76
	v_mov_b32_e32 v1, s77
	v_lshlrev_b64 v[0:1], 8, v[0:1]
	v_lshl_add_u64 v[0:1], v[134:135], 0, v[0:1]
	global_load_dwordx4 v[0:3], v[0:1], off
	v_lshlrev_b32_e32 v4, s86, v149
	v_sub_u32_e32 v4, s2, v4
	v_cmp_gt_i32_e32 vcc, s81, v4
	s_and_b64 s[78:79], s[10:11], vcc
	v_mov_b32_e32 v144, 0
	v_mov_b32_e32 v146, 0
	s_and_saveexec_b64 s[0:1], s[78:79]
	ds_read_b32 v146, v217 offset:272
	s_or_b64 exec, exec, s[0:1]
	v_med3_i32 v4, v4, 0, v212
	v_lshl_or_b32 v4, v4, 4, s76
	v_mov_b32_e32 v5, s77
	v_lshlrev_b64 v[4:5], 8, v[4:5]
	v_lshl_add_u64 v[4:5], v[134:135], 0, v[4:5]
	global_load_dwordx4 v[4:7], v[4:5], off
	v_lshlrev_b32_e32 v8, s86, v151
	v_sub_u32_e32 v8, s2, v8
	v_cmp_gt_i32_e32 vcc, s81, v8
	s_and_b64 s[78:79], s[12:13], vcc
	s_and_saveexec_b64 s[0:1], s[78:79]
	ds_read_b32 v144, v217 offset:288
	s_or_b64 exec, exec, s[0:1]
	v_med3_i32 v8, v8, 0, v212
	v_lshl_or_b32 v8, v8, 4, s76
	v_mov_b32_e32 v9, s77
	v_lshlrev_b64 v[8:9], 8, v[8:9]
	v_lshl_add_u64 v[8:9], v[134:135], 0, v[8:9]
	global_load_dwordx4 v[8:11], v[8:9], off
	v_lshlrev_b32_e32 v12, s86, v153
	v_sub_u32_e32 v12, s2, v12
	v_cmp_gt_i32_e32 vcc, s81, v12
	s_and_b64 s[78:79], s[14:15], vcc
	v_mov_b32_e32 v148, 0
	v_mov_b32_e32 v150, 0
	s_and_saveexec_b64 s[0:1], s[78:79]
	ds_read_b32 v150, v217 offset:304
	s_or_b64 exec, exec, s[0:1]
	v_med3_i32 v12, v12, 0, v212
	v_lshl_or_b32 v12, v12, 4, s76
	v_mov_b32_e32 v13, s77
	v_lshlrev_b64 v[12:13], 8, v[12:13]
	v_lshl_add_u64 v[12:13], v[134:135], 0, v[12:13]
	global_load_dwordx4 v[12:15], v[12:13], off
	v_lshlrev_b32_e32 v16, s86, v155
	v_sub_u32_e32 v16, s2, v16
	v_cmp_gt_i32_e32 vcc, s81, v16
	s_and_b64 s[78:79], s[16:17], vcc
	s_and_saveexec_b64 s[0:1], s[78:79]
	ds_read_b32 v148, v217 offset:320
	s_or_b64 exec, exec, s[0:1]
	v_med3_i32 v16, v16, 0, v212
	v_lshl_or_b32 v16, v16, 4, s76
	v_mov_b32_e32 v17, s77
	v_lshlrev_b64 v[16:17], 8, v[16:17]
	v_lshl_add_u64 v[16:17], v[134:135], 0, v[16:17]
	global_load_dwordx4 v[16:19], v[16:17], off
	v_lshlrev_b32_e32 v20, s86, v157
	v_sub_u32_e32 v20, s2, v20
	v_cmp_gt_i32_e32 vcc, s81, v20
	s_and_b64 s[78:79], s[18:19], vcc
	v_mov_b32_e32 v152, 0
	v_mov_b32_e32 v154, 0
	s_and_saveexec_b64 s[0:1], s[78:79]
	ds_read_b32 v154, v217 offset:336
	s_or_b64 exec, exec, s[0:1]
	v_med3_i32 v20, v20, 0, v212
	v_lshl_or_b32 v20, v20, 4, s76
	v_mov_b32_e32 v21, s77
	v_lshlrev_b64 v[20:21], 8, v[20:21]
	v_lshl_add_u64 v[20:21], v[134:135], 0, v[20:21]
	global_load_dwordx4 v[20:23], v[20:21], off
	v_lshlrev_b32_e32 v24, s86, v159
	v_sub_u32_e32 v24, s2, v24
	v_cmp_gt_i32_e32 vcc, s81, v24
	s_and_b64 s[78:79], s[20:21], vcc
	s_and_saveexec_b64 s[0:1], s[78:79]
	ds_read_b32 v152, v217 offset:352
	s_or_b64 exec, exec, s[0:1]
	v_med3_i32 v24, v24, 0, v212
	v_lshl_or_b32 v24, v24, 4, s76
	v_mov_b32_e32 v25, s77
	v_lshlrev_b64 v[24:25], 8, v[24:25]
	v_lshl_add_u64 v[24:25], v[134:135], 0, v[24:25]
	global_load_dwordx4 v[24:27], v[24:25], off
	v_lshlrev_b32_e32 v28, s86, v161
	v_sub_u32_e32 v28, s2, v28
	v_cmp_gt_i32_e32 vcc, s81, v28
	s_and_b64 s[78:79], s[22:23], vcc
	v_mov_b32_e32 v156, 0
	v_mov_b32_e32 v158, 0
	s_and_saveexec_b64 s[0:1], s[78:79]
	ds_read_b32 v158, v217 offset:368
	s_or_b64 exec, exec, s[0:1]
	v_med3_i32 v28, v28, 0, v212
	v_lshl_or_b32 v28, v28, 4, s76
	v_mov_b32_e32 v29, s77
	v_lshlrev_b64 v[28:29], 8, v[28:29]
	v_lshl_add_u64 v[28:29], v[134:135], 0, v[28:29]
	global_load_dwordx4 v[28:31], v[28:29], off
	v_lshlrev_b32_e32 v32, s86, v163
	v_sub_u32_e32 v32, s2, v32
	v_cmp_gt_i32_e32 vcc, s81, v32
	s_and_b64 s[78:79], s[24:25], vcc
	s_and_saveexec_b64 s[0:1], s[78:79]
	ds_read_b32 v156, v217 offset:384
	s_or_b64 exec, exec, s[0:1]
	v_med3_i32 v32, v32, 0, v212
	v_lshl_or_b32 v32, v32, 4, s76
	v_mov_b32_e32 v33, s77
	v_lshlrev_b64 v[32:33], 8, v[32:33]
	v_lshl_add_u64 v[32:33], v[134:135], 0, v[32:33]
	global_load_dwordx4 v[32:35], v[32:33], off
	v_lshlrev_b32_e32 v36, s86, v165
	v_sub_u32_e32 v36, s2, v36
	v_cmp_gt_i32_e32 vcc, s81, v36
	s_and_b64 s[78:79], s[26:27], vcc
	v_mov_b32_e32 v162, 0
	v_mov_b32_e32 v164, 0
	s_and_saveexec_b64 s[0:1], s[78:79]
	ds_read_b32 v164, v217 offset:400
	s_or_b64 exec, exec, s[0:1]
	v_med3_i32 v36, v36, 0, v212
	v_lshl_or_b32 v36, v36, 4, s76
	v_mov_b32_e32 v37, s77
	v_lshlrev_b64 v[36:37], 8, v[36:37]
	v_lshl_add_u64 v[36:37], v[134:135], 0, v[36:37]
	global_load_dwordx4 v[36:39], v[36:37], off
	v_lshlrev_b32_e32 v40, s86, v167
	v_sub_u32_e32 v40, s2, v40
	v_cmp_gt_i32_e32 vcc, s81, v40
	s_and_b64 s[78:79], s[28:29], vcc
	s_and_saveexec_b64 s[0:1], s[78:79]
	ds_read_b32 v162, v217 offset:416
	s_or_b64 exec, exec, s[0:1]
	v_med3_i32 v40, v40, 0, v212
	v_lshl_or_b32 v40, v40, 4, s76
	v_mov_b32_e32 v41, s77
	v_lshlrev_b64 v[40:41], 8, v[40:41]
	v_lshl_add_u64 v[40:41], v[134:135], 0, v[40:41]
	global_load_dwordx4 v[40:43], v[40:41], off
	v_lshlrev_b32_e32 v44, s86, v169
	v_sub_u32_e32 v44, s2, v44
	v_cmp_gt_i32_e32 vcc, s81, v44
	s_and_b64 s[78:79], s[30:31], vcc
	v_mov_b32_e32 v166, 0
	v_mov_b32_e32 v168, 0
	s_and_saveexec_b64 s[0:1], s[78:79]
	ds_read_b32 v168, v217 offset:432
	s_or_b64 exec, exec, s[0:1]
	v_med3_i32 v44, v44, 0, v212
	v_lshl_or_b32 v44, v44, 4, s76
	v_mov_b32_e32 v45, s77
	v_lshlrev_b64 v[44:45], 8, v[44:45]
; DI void attn_sample_unit(const Params& p, int u, const bf16_t* Q, const bf16_t* Kb, const bf16_t* Vb, bf16_t* att, LAS float* sl, int lane) {
;     ...
;         for (int jj = 0; jj < 33; ++jj) { const int j = kg + 4 * jj; int idx = 2048 + t - dil * j; const bool use = (j <= 128) && (idx < 2048);
;             idx = idx < 0 ? 0 : (idx > 2047 ? 2047 : idx); const float pv = use ? sl[64 + pat * 192 + (j > 128 ? 128 : j)] : 0.f;
;             const f32x4 vv = *(const f32x4*)(cv + (((size_t)b * 2048 + idx) * 16 + h) * 64 + 4 * d4);
;             acc += vv * pv; }
	v_lshl_add_u64 v[44:45], v[134:135], 0, v[44:45]
	global_load_dwordx4 v[44:47], v[44:45], off
	v_lshlrev_b32_e32 v48, s86, v171
	v_sub_u32_e32 v48, s2, v48
	v_cmp_gt_i32_e32 vcc, s81, v48
	s_and_b64 s[78:79], s[34:35], vcc
	s_and_saveexec_b64 s[0:1], s[78:79]
	ds_read_b32 v166, v217 offset:448
	s_or_b64 exec, exec, s[0:1]
	v_med3_i32 v48, v48, 0, v212
	v_lshl_or_b32 v48, v48, 4, s76
	v_mov_b32_e32 v49, s77
	v_lshlrev_b64 v[48:49], 8, v[48:49]
	v_lshl_add_u64 v[48:49], v[134:135], 0, v[48:49]
	global_load_dwordx4 v[48:51], v[48:49], off
	v_lshlrev_b32_e32 v52, s86, v173
	v_sub_u32_e32 v52, s2, v52
	v_cmp_gt_i32_e32 vcc, s81, v52
	s_and_b64 s[78:79], s[36:37], vcc
	v_mov_b32_e32 v170, 0
	v_mov_b32_e32 v172, 0
	s_and_saveexec_b64 s[0:1], s[78:79]
	ds_read_b32 v172, v217 offset:464
	s_or_b64 exec, exec, s[0:1]
	v_med3_i32 v52, v52, 0, v212
	v_lshl_or_b32 v52, v52, 4, s76
	v_mov_b32_e32 v53, s77
	v_lshlrev_b64 v[52:53], 8, v[52:53]
	v_lshl_add_u64 v[52:53], v[134:135], 0, v[52:53]
	global_load_dwordx4 v[52:55], v[52:53], off
	v_lshlrev_b32_e32 v56, s86, v175
	v_sub_u32_e32 v56, s2, v56
	v_cmp_gt_i32_e32 vcc, s81, v56
	s_and_b64 s[78:79], s[38:39], vcc
	s_and_saveexec_b64 s[0:1], s[78:79]
	ds_read_b32 v170, v217 offset:480
	s_or_b64 exec, exec, s[0:1]
	v_med3_i32 v56, v56, 0, v212
	v_lshl_or_b32 v56, v56, 4, s76
	v_mov_b32_e32 v57, s77
	v_lshlrev_b64 v[56:57], 8, v[56:57]
	v_lshl_add_u64 v[56:57], v[134:135], 0, v[56:57]
	global_load_dwordx4 v[56:59], v[56:57], off
	v_lshlrev_b32_e32 v60, s86, v177
	v_sub_u32_e32 v60, s2, v60
	v_cmp_gt_i32_e32 vcc, s81, v60
	s_and_b64 s[78:79], s[40:41], vcc
	v_mov_b32_e32 v174, 0
	v_mov_b32_e32 v176, 0
	s_and_saveexec_b64 s[0:1], s[78:79]
	ds_read_b32 v176, v217 offset:496
	s_or_b64 exec, exec, s[0:1]
	v_med3_i32 v60, v60, 0, v212
	v_lshl_or_b32 v60, v60, 4, s76
	v_mov_b32_e32 v61, s77
	v_lshlrev_b64 v[60:61], 8, v[60:61]
	v_lshl_add_u64 v[60:61], v[134:135], 0, v[60:61]
	global_load_dwordx4 v[60:63], v[60:61], off
	v_lshlrev_b32_e32 v64, s86, v179
	v_sub_u32_e32 v64, s2, v64
	v_cmp_gt_i32_e32 vcc, s81, v64
	s_and_b64 s[78:79], s[42:43], vcc
	s_and_saveexec_b64 s[0:1], s[78:79]
	ds_read_b32 v174, v217 offset:512
	s_or_b64 exec, exec, s[0:1]
	v_med3_i32 v64, v64, 0, v212
	v_lshl_or_b32 v64, v64, 4, s76
	v_mov_b32_e32 v65, s77
	v_lshlrev_b64 v[64:65], 8, v[64:65]
	v_lshl_add_u64 v[64:65], v[134:135], 0, v[64:65]
	global_load_dwordx4 v[64:67], v[64:65], off
	v_lshlrev_b32_e32 v68, s86, v181
	v_sub_u32_e32 v68, s2, v68
	v_cmp_gt_i32_e32 vcc, s81, v68
	s_and_b64 s[78:79], s[44:45], vcc
	v_mov_b32_e32 v178, 0
	v_mov_b32_e32 v180, 0
	s_and_saveexec_b64 s[0:1], s[78:79]
	ds_read_b32 v180, v217 offset:528
	s_or_b64 exec, exec, s[0:1]
	v_med3_i32 v68, v68, 0, v212
	v_lshl_or_b32 v68, v68, 4, s76
	v_mov_b32_e32 v69, s77
	v_lshlrev_b64 v[68:69], 8, v[68:69]
	v_lshl_add_u64 v[68:69], v[134:135], 0, v[68:69]
	global_load_dwordx4 v[68:71], v[68:69], off
	v_lshlrev_b32_e32 v72, s86, v183
	v_sub_u32_e32 v72, s2, v72
	v_cmp_gt_i32_e32 vcc, s81, v72
	s_and_b64 s[78:79], s[46:47], vcc
	s_and_saveexec_b64 s[0:1], s[78:79]
	ds_read_b32 v178, v217 offset:544
	s_or_b64 exec, exec, s[0:1]
	v_med3_i32 v72, v72, 0, v212
	v_lshl_or_b32 v72, v72, 4, s76
	v_mov_b32_e32 v73, s77
	v_lshlrev_b64 v[72:73], 8, v[72:73]
	v_lshl_add_u64 v[72:73], v[134:135], 0, v[72:73]
	global_load_dwordx4 v[72:75], v[72:73], off
	v_lshlrev_b32_e32 v76, s86, v185
	v_sub_u32_e32 v76, s2, v76
	v_cmp_gt_i32_e32 vcc, s81, v76
	s_and_b64 s[78:79], s[48:49], vcc
	v_mov_b32_e32 v182, 0
	v_mov_b32_e32 v184, 0
	s_and_saveexec_b64 s[0:1], s[78:79]
	ds_read_b32 v184, v217 offset:560
	s_or_b64 exec, exec, s[0:1]
	v_med3_i32 v76, v76, 0, v212
	v_lshl_or_b32 v76, v76, 4, s76
	v_mov_b32_e32 v77, s77
	v_lshlrev_b64 v[76:77], 8, v[76:77]
	v_lshl_add_u64 v[76:77], v[134:135], 0, v[76:77]
	global_load_dwordx4 v[76:79], v[76:77], off
	v_lshlrev_b32_e32 v80, s86, v187
	v_sub_u32_e32 v80, s2, v80
	v_cmp_gt_i32_e32 vcc, s81, v80
	s_and_b64 s[78:79], s[50:51], vcc
	s_and_saveexec_b64 s[0:1], s[78:79]
	ds_read_b32 v182, v217 offset:576
	s_or_b64 exec, exec, s[0:1]
	v_med3_i32 v80, v80, 0, v212
	v_lshl_or_b32 v80, v80, 4, s76
	v_mov_b32_e32 v81, s77
	v_lshlrev_b64 v[80:81], 8, v[80:81]
	v_lshl_add_u64 v[80:81], v[134:135], 0, v[80:81]
	global_load_dwordx4 v[80:83], v[80:81], off
	v_lshlrev_b32_e32 v84, s86, v189
	v_sub_u32_e32 v84, s2, v84
	v_cmp_gt_i32_e32 vcc, s81, v84
	s_and_b64 s[78:79], s[52:53], vcc
	v_mov_b32_e32 v186, 0
	v_mov_b32_e32 v188, 0
	s_and_saveexec_b64 s[0:1], s[78:79]
	ds_read_b32 v188, v217 offset:592
	s_or_b64 exec, exec, s[0:1]
	v_med3_i32 v84, v84, 0, v212
	v_lshl_or_b32 v84, v84, 4, s76
	v_mov_b32_e32 v85, s77
	v_lshlrev_b64 v[84:85], 8, v[84:85]
	v_lshl_add_u64 v[84:85], v[134:135], 0, v[84:85]
	global_load_dwordx4 v[84:87], v[84:85], off
	v_lshlrev_b32_e32 v88, s86, v191
	v_sub_u32_e32 v88, s2, v88
	v_cmp_gt_i32_e32 vcc, s81, v88
	s_and_b64 s[78:79], s[54:55], vcc
	s_and_saveexec_b64 s[0:1], s[78:79]
	ds_read_b32 v186, v217 offset:608
	s_or_b64 exec, exec, s[0:1]
	v_med3_i32 v88, v88, 0, v212
	v_lshl_or_b32 v88, v88, 4, s76
	v_mov_b32_e32 v89, s77
	v_lshlrev_b64 v[88:89], 8, v[88:89]
	v_lshl_add_u64 v[88:89], v[134:135], 0, v[88:89]
	global_load_dwordx4 v[88:91], v[88:89], off
	v_lshlrev_b32_e32 v92, s86, v193
	v_sub_u32_e32 v92, s2, v92
	v_cmp_gt_i32_e32 vcc, s81, v92
	s_and_b64 s[78:79], s[56:57], vcc
	v_mov_b32_e32 v190, 0
	v_mov_b32_e32 v192, 0
	s_and_saveexec_b64 s[0:1], s[78:79]
	ds_read_b32 v192, v217 offset:624
	s_or_b64 exec, exec, s[0:1]
	v_med3_i32 v92, v92, 0, v212
	v_lshl_or_b32 v92, v92, 4, s76
	v_mov_b32_e32 v93, s77
	v_lshlrev_b64 v[92:93], 8, v[92:93]
; DI void attn_sample_unit(const Params& p, int u, const bf16_t* Q, const bf16_t* Kb, const bf16_t* Vb, bf16_t* att, LAS float* sl, int lane) {
;     ...
;         for (int jj = 0; jj < 33; ++jj) { const int j = kg + 4 * jj; int idx = 2048 + t - dil * j; const bool use = (j <= 128) && (idx < 2048);
;             idx = idx < 0 ? 0 : (idx > 2047 ? 2047 : idx); const float pv = use ? sl[64 + pat * 192 + (j > 128 ? 128 : j)] : 0.f;
;             const f32x4 vv = *(const f32x4*)(cv + (((size_t)b * 2048 + idx) * 16 + h) * 64 + 4 * d4);
;             acc += vv * pv; }
	v_lshl_add_u64 v[92:93], v[134:135], 0, v[92:93]
	global_load_dwordx4 v[92:95], v[92:93], off
	v_lshlrev_b32_e32 v96, s86, v195
	v_sub_u32_e32 v96, s2, v96
	v_cmp_gt_i32_e32 vcc, s81, v96
	s_and_b64 s[78:79], s[58:59], vcc
	s_and_saveexec_b64 s[0:1], s[78:79]
	ds_read_b32 v190, v217 offset:640
	s_or_b64 exec, exec, s[0:1]
	v_med3_i32 v96, v96, 0, v212
	v_lshl_or_b32 v96, v96, 4, s76
	v_mov_b32_e32 v97, s77
	v_lshlrev_b64 v[96:97], 8, v[96:97]
	v_lshl_add_u64 v[96:97], v[134:135], 0, v[96:97]
	global_load_dwordx4 v[96:99], v[96:97], off
	v_lshlrev_b32_e32 v100, s86, v197
	v_sub_u32_e32 v100, s2, v100
	v_cmp_gt_i32_e32 vcc, s81, v100
	s_and_b64 s[78:79], s[60:61], vcc
	v_mov_b32_e32 v194, 0
	v_mov_b32_e32 v196, 0
	s_and_saveexec_b64 s[0:1], s[78:79]
	ds_read_b32 v196, v217 offset:656
	s_or_b64 exec, exec, s[0:1]
	v_med3_i32 v100, v100, 0, v212
	v_lshl_or_b32 v100, v100, 4, s76
	v_mov_b32_e32 v101, s77
	v_lshlrev_b64 v[100:101], 8, v[100:101]
	v_lshl_add_u64 v[100:101], v[134:135], 0, v[100:101]
	global_load_dwordx4 v[100:103], v[100:101], off
	v_lshlrev_b32_e32 v104, s86, v199
	v_sub_u32_e32 v104, s2, v104
	v_cmp_gt_i32_e32 vcc, s81, v104
	s_and_b64 s[78:79], s[62:63], vcc
	s_and_saveexec_b64 s[0:1], s[78:79]
	ds_read_b32 v194, v217 offset:672
	s_or_b64 exec, exec, s[0:1]
	v_med3_i32 v104, v104, 0, v212
	v_lshl_or_b32 v104, v104, 4, s76
	v_mov_b32_e32 v105, s77
	v_lshlrev_b64 v[104:105], 8, v[104:105]
	v_lshl_add_u64 v[104:105], v[134:135], 0, v[104:105]
	global_load_dwordx4 v[104:107], v[104:105], off
	v_lshlrev_b32_e32 v108, s86, v201
	v_sub_u32_e32 v108, s2, v108
	v_cmp_gt_i32_e32 vcc, s81, v108
	s_and_b64 s[78:79], s[64:65], vcc
	v_mov_b32_e32 v198, 0
	v_mov_b32_e32 v200, 0
	s_and_saveexec_b64 s[0:1], s[78:79]
	ds_read_b32 v200, v217 offset:688
	s_or_b64 exec, exec, s[0:1]
	v_med3_i32 v108, v108, 0, v212
	v_lshl_or_b32 v108, v108, 4, s76
	v_mov_b32_e32 v109, s77
	v_lshlrev_b64 v[108:109], 8, v[108:109]
	v_lshl_add_u64 v[108:109], v[134:135], 0, v[108:109]
	global_load_dwordx4 v[108:111], v[108:109], off
	v_lshlrev_b32_e32 v112, s86, v203
	v_sub_u32_e32 v112, s2, v112
	v_cmp_gt_i32_e32 vcc, s81, v112
	s_and_b64 s[78:79], s[66:67], vcc
	s_and_saveexec_b64 s[0:1], s[78:79]
	ds_read_b32 v198, v217 offset:704
	s_or_b64 exec, exec, s[0:1]
	v_med3_i32 v112, v112, 0, v212
	v_lshl_or_b32 v112, v112, 4, s76
	v_mov_b32_e32 v113, s77
	v_lshlrev_b64 v[112:113], 8, v[112:113]
	v_lshl_add_u64 v[112:113], v[134:135], 0, v[112:113]
	global_load_dwordx4 v[112:115], v[112:113], off
	v_lshlrev_b32_e32 v116, s86, v205
	v_sub_u32_e32 v116, s2, v116
	v_cmp_gt_i32_e32 vcc, s81, v116
	s_and_b64 s[78:79], s[68:69], vcc
	v_mov_b32_e32 v202, 0
	v_mov_b32_e32 v204, 0
	s_and_saveexec_b64 s[0:1], s[78:79]
	ds_read_b32 v204, v217 offset:720
	s_or_b64 exec, exec, s[0:1]
	v_med3_i32 v116, v116, 0, v212
	v_lshl_or_b32 v116, v116, 4, s76
	v_mov_b32_e32 v117, s77
	v_lshlrev_b64 v[116:117], 8, v[116:117]
	v_lshl_add_u64 v[116:117], v[134:135], 0, v[116:117]
	global_load_dwordx4 v[116:119], v[116:117], off
	v_lshlrev_b32_e32 v120, s86, v207
	v_sub_u32_e32 v120, s2, v120
	v_cmp_gt_i32_e32 vcc, s81, v120
	s_and_b64 s[78:79], s[70:71], vcc
	s_and_saveexec_b64 s[0:1], s[78:79]
	ds_read_b32 v202, v217 offset:736
	s_or_b64 exec, exec, s[0:1]
	v_med3_i32 v120, v120, 0, v212
	v_lshl_or_b32 v120, v120, 4, s76
	v_mov_b32_e32 v121, s77
	v_lshlrev_b64 v[120:121], 8, v[120:121]
	v_lshl_add_u64 v[120:121], v[134:135], 0, v[120:121]
	global_load_dwordx4 v[120:123], v[120:121], off
	v_lshlrev_b32_e32 v124, s86, v208
	v_sub_u32_e32 v124, s2, v124
	v_cmp_gt_i32_e32 vcc, s81, v124
	s_and_b64 s[78:79], s[72:73], vcc
	v_mov_b32_e32 v160, 0
	v_mov_b32_e32 v206, 0
	s_and_saveexec_b64 s[0:1], s[78:79]
	ds_read_b32 v206, v217 offset:752
	s_or_b64 exec, exec, s[0:1]
	v_med3_i32 v124, v124, 0, v212
	v_lshl_or_b32 v124, v124, 4, s76
	v_mov_b32_e32 v125, s77
	v_lshlrev_b64 v[124:125], 8, v[124:125]
	v_lshl_add_u64 v[124:125], v[134:135], 0, v[124:125]
	global_load_dwordx4 v[124:127], v[124:125], off
	v_lshlrev_b32_e32 v218, s86, v209
	v_sub_u32_e32 v218, s2, v218
	v_med3_i32 v220, v218, 0, v212
	v_lshl_or_b32 v220, v220, 4, s76
	v_mov_b32_e32 v221, s77
	v_lshlrev_b64 v[220:221], 8, v[220:221]
	v_lshl_add_u64 v[220:221], v[134:135], 0, v[220:221]
	global_load_dwordx4 v[224:227], v[220:221], off
	v_cmp_gt_i32_e32 vcc, s81, v218
	s_and_b64 s[78:79], s[74:75], vcc
	s_and_saveexec_b64 s[0:1], s[78:79]
	ds_read_b32 v160, v217 offset:768
	s_or_b64 exec, exec, s[0:1]
	s_waitcnt vmcnt(32) lgkmcnt(0)
	v_pk_fma_f32 v[2:3], v[2:3], v[132:133], v[142:143] op_sel_hi:[1,0,1]
	v_pk_fma_f32 v[0:1], v[0:1], v[132:133], v[140:141] op_sel_hi:[1,0,1]
	s_waitcnt vmcnt(31)
	v_pk_fma_f32 v[2:3], v[6:7], v[146:147], v[2:3] op_sel_hi:[1,0,1]
	v_pk_fma_f32 v[0:1], v[4:5], v[146:147], v[0:1] op_sel_hi:[1,0,1]
	s_waitcnt vmcnt(30)
	v_pk_fma_f32 v[2:3], v[10:11], v[144:145], v[2:3] op_sel_hi:[1,0,1]
	v_pk_fma_f32 v[0:1], v[8:9], v[144:145], v[0:1] op_sel_hi:[1,0,1]
	s_waitcnt vmcnt(29)
	v_pk_fma_f32 v[2:3], v[14:15], v[150:151], v[2:3] op_sel_hi:[1,0,1]
	v_pk_fma_f32 v[0:1], v[12:13], v[150:151], v[0:1] op_sel_hi:[1,0,1]
	s_waitcnt vmcnt(28)
	v_pk_fma_f32 v[2:3], v[18:19], v[148:149], v[2:3] op_sel_hi:[1,0,1]
	v_pk_fma_f32 v[0:1], v[16:17], v[148:149], v[0:1] op_sel_hi:[1,0,1]
	s_waitcnt vmcnt(27)
	v_pk_fma_f32 v[2:3], v[22:23], v[154:155], v[2:3] op_sel_hi:[1,0,1]
	v_pk_fma_f32 v[0:1], v[20:21], v[154:155], v[0:1] op_sel_hi:[1,0,1]
	s_waitcnt vmcnt(26)
; DI float bflo(unsigned w) { return __uint_as_float(w << 16); }
; DI float bfhi(unsigned w) { return __uint_as_float(w & 0xffff0000u); }
; DI void attn_sample_unit(const Params& p, int u, const bf16_t* Q, const bf16_t* Kb, const bf16_t* Vb, bf16_t* att, LAS float* sl, int lane) {
;     ...
;     { const int kg = lane >> 4, d4 = lane & 15; f32x4 acc = (f32x4){0.f, 0.f, 0.f, 0.f};
; #pragma unroll 1
;       for (int pat = 0; pat < 3; ++pat) { const int dil = 1 << (2 * pat);
; #pragma unroll
;         for (int jj = 0; jj < 33; ++jj) { const int j = kg + 4 * jj; int idx = 2048 + t - dil * j; const bool use = (j <= 128) && (idx < 2048);
;             idx = idx < 0 ? 0 : (idx > 2047 ? 2047 : idx); const float pv = use ? sl[64 + pat * 192 + (j > 128 ? 128 : j)] : 0.f;
;             const f32x4 vv = *(const f32x4*)(cv + (((size_t)b * 2048 + idx) * 16 + h) * 64 + 4 * d4);
;             acc += vv * pv; }
;         if (kg == 0) { for (int j = 0; dil * j <= t; ++j) { const int idx = 2048 + t - dil * j; const float pv = sl[64 + pat * 192 + j];
;             const u32x2 w = *(const u32x2*)(Vb + ((size_t)NP + b * 4 + (idx - 2048)) * 1024 + h * 64 + 4 * d4);
;             acc += (f32x4){bflo(w.x), bfhi(w.x), bflo(w.y), bfhi(w.y)} * pv; } } }
	v_pk_fma_f32 v[2:3], v[26:27], v[152:153], v[2:3] op_sel_hi:[1,0,1]
	v_pk_fma_f32 v[0:1], v[24:25], v[152:153], v[0:1] op_sel_hi:[1,0,1]
	s_waitcnt vmcnt(25)
	v_pk_fma_f32 v[2:3], v[30:31], v[158:159], v[2:3] op_sel_hi:[1,0,1]
	v_pk_fma_f32 v[0:1], v[28:29], v[158:159], v[0:1] op_sel_hi:[1,0,1]
	s_waitcnt vmcnt(24)
	v_pk_fma_f32 v[2:3], v[34:35], v[156:157], v[2:3] op_sel_hi:[1,0,1]
	v_pk_fma_f32 v[0:1], v[32:33], v[156:157], v[0:1] op_sel_hi:[1,0,1]
	s_waitcnt vmcnt(23)
	v_pk_fma_f32 v[2:3], v[38:39], v[164:165], v[2:3] op_sel_hi:[1,0,1]
	v_pk_fma_f32 v[0:1], v[36:37], v[164:165], v[0:1] op_sel_hi:[1,0,1]
	s_waitcnt vmcnt(22)
	v_pk_fma_f32 v[2:3], v[42:43], v[162:163], v[2:3] op_sel_hi:[1,0,1]
	v_pk_fma_f32 v[0:1], v[40:41], v[162:163], v[0:1] op_sel_hi:[1,0,1]
	s_waitcnt vmcnt(21)
	v_pk_fma_f32 v[2:3], v[46:47], v[168:169], v[2:3] op_sel_hi:[1,0,1]
	v_pk_fma_f32 v[0:1], v[44:45], v[168:169], v[0:1] op_sel_hi:[1,0,1]
	s_waitcnt vmcnt(20)
	v_pk_fma_f32 v[2:3], v[50:51], v[166:167], v[2:3] op_sel_hi:[1,0,1]
	v_pk_fma_f32 v[0:1], v[48:49], v[166:167], v[0:1] op_sel_hi:[1,0,1]
	s_waitcnt vmcnt(19)
	v_pk_fma_f32 v[2:3], v[54:55], v[172:173], v[2:3] op_sel_hi:[1,0,1]
	v_pk_fma_f32 v[0:1], v[52:53], v[172:173], v[0:1] op_sel_hi:[1,0,1]
	s_waitcnt vmcnt(18)
	v_pk_fma_f32 v[2:3], v[58:59], v[170:171], v[2:3] op_sel_hi:[1,0,1]
	v_pk_fma_f32 v[0:1], v[56:57], v[170:171], v[0:1] op_sel_hi:[1,0,1]
	s_waitcnt vmcnt(17)
	v_pk_fma_f32 v[2:3], v[62:63], v[176:177], v[2:3] op_sel_hi:[1,0,1]
	v_pk_fma_f32 v[0:1], v[60:61], v[176:177], v[0:1] op_sel_hi:[1,0,1]
	s_waitcnt vmcnt(16)
	v_pk_fma_f32 v[2:3], v[66:67], v[174:175], v[2:3] op_sel_hi:[1,0,1]
	v_pk_fma_f32 v[0:1], v[64:65], v[174:175], v[0:1] op_sel_hi:[1,0,1]
	s_waitcnt vmcnt(15)
	v_pk_fma_f32 v[2:3], v[70:71], v[180:181], v[2:3] op_sel_hi:[1,0,1]
	v_pk_fma_f32 v[0:1], v[68:69], v[180:181], v[0:1] op_sel_hi:[1,0,1]
	s_waitcnt vmcnt(14)
	v_pk_fma_f32 v[2:3], v[74:75], v[178:179], v[2:3] op_sel_hi:[1,0,1]
	v_pk_fma_f32 v[0:1], v[72:73], v[178:179], v[0:1] op_sel_hi:[1,0,1]
	s_waitcnt vmcnt(13)
	v_pk_fma_f32 v[2:3], v[78:79], v[184:185], v[2:3] op_sel_hi:[1,0,1]
	v_pk_fma_f32 v[0:1], v[76:77], v[184:185], v[0:1] op_sel_hi:[1,0,1]
	s_waitcnt vmcnt(12)
	v_pk_fma_f32 v[2:3], v[82:83], v[182:183], v[2:3] op_sel_hi:[1,0,1]
	v_pk_fma_f32 v[0:1], v[80:81], v[182:183], v[0:1] op_sel_hi:[1,0,1]
	s_waitcnt vmcnt(11)
	v_pk_fma_f32 v[2:3], v[86:87], v[188:189], v[2:3] op_sel_hi:[1,0,1]
	v_pk_fma_f32 v[0:1], v[84:85], v[188:189], v[0:1] op_sel_hi:[1,0,1]
	s_waitcnt vmcnt(10)
	v_pk_fma_f32 v[2:3], v[90:91], v[186:187], v[2:3] op_sel_hi:[1,0,1]
	v_pk_fma_f32 v[0:1], v[88:89], v[186:187], v[0:1] op_sel_hi:[1,0,1]
	s_waitcnt vmcnt(9)
	v_pk_fma_f32 v[2:3], v[94:95], v[192:193], v[2:3] op_sel_hi:[1,0,1]
	v_pk_fma_f32 v[0:1], v[92:93], v[192:193], v[0:1] op_sel_hi:[1,0,1]
	s_waitcnt vmcnt(8)
	v_pk_fma_f32 v[2:3], v[98:99], v[190:191], v[2:3] op_sel_hi:[1,0,1]
	v_pk_fma_f32 v[0:1], v[96:97], v[190:191], v[0:1] op_sel_hi:[1,0,1]
	s_waitcnt vmcnt(7)
	v_pk_fma_f32 v[2:3], v[102:103], v[196:197], v[2:3] op_sel_hi:[1,0,1]
	v_pk_fma_f32 v[0:1], v[100:101], v[196:197], v[0:1] op_sel_hi:[1,0,1]
	s_waitcnt vmcnt(6)
	v_pk_fma_f32 v[2:3], v[106:107], v[194:195], v[2:3] op_sel_hi:[1,0,1]
	v_pk_fma_f32 v[0:1], v[104:105], v[194:195], v[0:1] op_sel_hi:[1,0,1]
	s_waitcnt vmcnt(5)
	v_pk_fma_f32 v[2:3], v[110:111], v[200:201], v[2:3] op_sel_hi:[1,0,1]
	v_pk_fma_f32 v[0:1], v[108:109], v[200:201], v[0:1] op_sel_hi:[1,0,1]
	s_waitcnt vmcnt(4)
	v_pk_fma_f32 v[2:3], v[114:115], v[198:199], v[2:3] op_sel_hi:[1,0,1]
	v_pk_fma_f32 v[0:1], v[112:113], v[198:199], v[0:1] op_sel_hi:[1,0,1]
	s_waitcnt vmcnt(3)
	v_pk_fma_f32 v[2:3], v[118:119], v[204:205], v[2:3] op_sel_hi:[1,0,1]
	v_pk_fma_f32 v[0:1], v[116:117], v[204:205], v[0:1] op_sel_hi:[1,0,1]
	s_waitcnt vmcnt(2)
	v_pk_fma_f32 v[2:3], v[122:123], v[202:203], v[2:3] op_sel_hi:[1,0,1]
	v_pk_fma_f32 v[4:5], v[120:121], v[202:203], v[0:1] op_sel_hi:[1,0,1]
	s_waitcnt vmcnt(1)
	v_pk_fma_f32 v[0:1], v[126:127], v[206:207], v[2:3] op_sel_hi:[1,0,1]
	v_pk_fma_f32 v[2:3], v[124:125], v[206:207], v[4:5] op_sel_hi:[1,0,1]
	s_waitcnt vmcnt(0)
	v_pk_fma_f32 v[142:143], v[226:227], v[160:161], v[0:1] op_sel_hi:[1,0,1]
	v_pk_fma_f32 v[140:141], v[224:225], v[160:161], v[2:3] op_sel_hi:[1,0,1]
	s_and_saveexec_b64 s[0:1], s[6:7]
	s_cbranch_execz .LBB0_1534
	s_mov_b32 s89, 0
	s_mov_b32 s87, 1
	s_mov_b32 s88, s85
.LBB0_1603:
	s_sub_i32 s78, s84, s89
	s_and_b32 s78, s78, 3
	v_mov_b32_e32 v0, v228
	v_mov_b32_e32 v1, v229
	s_cmp_eq_u32 s78, 1
	s_cbranch_scc0 .Lvnt_a
	v_mov_b32_e32 v0, v230
	v_mov_b32_e32 v1, v231
.Lvnt_a:
	s_cmp_eq_u32 s78, 2
	s_cbranch_scc0 .Lvnt_b
	v_mov_b32_e32 v0, v232
	v_mov_b32_e32 v1, v233
.Lvnt_b:
	s_cmp_eq_u32 s78, 3
	s_cbranch_scc0 .Lvnt_c
	v_mov_b32_e32 v0, v234
	v_mov_b32_e32 v1, v235
.Lvnt_c:
	v_mov_b32_e32 v2, s88
	ds_read_b32 v2, v2
	s_lshl_b32 s89, s87, s86
	s_add_i32 s88, s88, 4
	s_add_i32 s87, s87, 1
	s_cmp_le_u32 s89, s4
	s_waitcnt vmcnt(0)
	v_lshlrev_b32_e32 v4, 16, v0
	v_and_b32_e32 v5, 0xffff0000, v0
	v_lshlrev_b32_e32 v0, 16, v1
	v_and_b32_e32 v1, 0xffff0000, v1
	s_waitcnt lgkmcnt(0)
	v_pk_fma_f32 v[142:143], v[2:3], v[0:1], v[142:143] op_sel_hi:[0,1,1]
	v_pk_fma_f32 v[140:141], v[2:3], v[4:5], v[140:141] op_sel_hi:[0,1,1]
	s_cbranch_scc1 .LBB0_1603
	s_branch .LBB0_1534
